# baseline (speedup 1.0000x reference)
; DEVI void hgrn_a_item(int TID_, int BID_, PREF p, int item, char* shm) {
;     ...
;   const int w = tid >> 6, lane = tid & 63, fr = lane & 15, fq = lane >> 4;
; #pragma unroll 1
;   for (int dir = 0; dir < 2; ++dir) {
;     f32x4 acc[8];
; #pragma unroll
;     for (int n = 0; n < 8; ++n) acc[n] = (f32x4){0.f, 0.f, 0.f, 0.f};
; #pragma unroll
;     for (int ks = 0; ks < 2; ++ks) {
;       bf16x8 a = *(const bf16x8*)(vT + (16 * w + fr) * 72 + ks * 32 + fq * 8);
; #pragma unroll
;       for (int n = 0; n < 8; ++n) {
;         bf16x8 b = *(const bf16x8*)(kdT + (size_t)(dir * 128 + 16 * n + fr) * 72 + ks * 32 + fq * 8);
;         acc[n] = __builtin_amdgcn_mfma_f32_16x16x32_bf16(a, b, acc[n], 0, 0, 0);
;       }
;     }
;     u16* dst = upd + ((size_t)(c * 8 + h) * 2 + dir) * 16384;
; #pragma unroll
;     for (int n = 0; n < 8; ++n)
; #pragma unroll
;       for (int r = 0; r < 4; ++r) dst[(16 * w + fq * 4 + r) * 128 + 16 * n + fr] = f2bf(acc[n][r]);
;   }
.LBB0_151:
	v_lshl_or_b32 v19, s19, 7, v13
	v_mad_u32_u24 v19, v19, s57, v16
	s_lshl_b32 s68, s19, 15
	s_mov_b32 s19, 1
	s_and_b64 vcc, exec, s[8:9]
	s_mov_b64 s[8:9], 0
	ds_read_b128 v[50:53], v19 offset:18432
	ds_read_b128 v[54:57], v19 offset:20736
	ds_read_b128 v[58:61], v19 offset:23040
	ds_read_b128 v[62:65], v19 offset:25344
	ds_read_b128 v[66:69], v19 offset:27648
	ds_read_b128 v[70:73], v19 offset:29952
	ds_read_b128 v[74:77], v19 offset:32256
	ds_read_b128 v[78:81], v19 offset:34560
	ds_read_b128 v[184:187], v19 offset:18496
	ds_read_b128 v[188:191], v19 offset:20800
	ds_read_b128 v[192:195], v19 offset:23104
	ds_read_b128 v[216:219], v19 offset:25408
	s_waitcnt lgkmcnt(4)
	v_mfma_f32_16x16x32_bf16 v[50:53], v[50:53], v[0:3], 0
	v_mfma_f32_16x16x32_bf16 v[54:57], v[54:57], v[0:3], 0
	v_mfma_f32_16x16x32_bf16 v[58:61], v[58:61], v[0:3], 0
	v_mfma_f32_16x16x32_bf16 v[62:65], v[62:65], v[0:3], 0
	v_mfma_f32_16x16x32_bf16 v[66:69], v[66:69], v[0:3], 0
	v_mfma_f32_16x16x32_bf16 v[70:73], v[70:73], v[0:3], 0
	v_mfma_f32_16x16x32_bf16 v[74:77], v[74:77], v[0:3], 0
	v_mfma_f32_16x16x32_bf16 v[78:81], v[78:81], v[0:3], 0
	ds_read_b128 v[220:223], v19 offset:27712
	ds_read_b128 v[224:227], v19 offset:30016
	ds_read_b128 v[228:231], v19 offset:32320
	ds_read_b128 v[232:235], v19 offset:34624
	s_waitcnt lgkmcnt(4)
	v_mfma_f32_16x16x32_bf16 v[50:53], v[184:187], v[4:7], v[50:53]
	v_mfma_f32_16x16x32_bf16 v[54:57], v[188:191], v[4:7], v[54:57]
	v_mfma_f32_16x16x32_bf16 v[58:61], v[192:195], v[4:7], v[58:61]
	v_mfma_f32_16x16x32_bf16 v[62:65], v[216:219], v[4:7], v[62:65]
	s_waitcnt lgkmcnt(0)
	v_mfma_f32_16x16x32_bf16 v[66:69], v[220:223], v[4:7], v[66:69]
	v_mfma_f32_16x16x32_bf16 v[70:73], v[224:227], v[4:7], v[70:73]
	v_mfma_f32_16x16x32_bf16 v[74:77], v[228:231], v[4:7], v[74:77]
	v_mfma_f32_16x16x32_bf16 v[78:81], v[232:235], v[4:7], v[78:81]
	v_and_b32_e32 v194, 15, v203
	v_lshl_add_u32 v194, s48, 4, v194
	v_lshlrev_b32_e32 v194, 8, v194
	v_lshrrev_b32_e32 v195, 4, v203
	v_lshl_add_u32 v194, v195, 3, v194
	v_mov_b32_e32 v195, v197
	v_lshl_add_u64 v[192:193], v[38:39], 0, s[68:69]
	v_lshl_add_u64 v[192:193], v[192:193], 0, v[194:195]
	v_cvt_pk_bf16_f32 v184, v50, v51
	v_cvt_pk_bf16_f32 v185, v52, v53
	global_store_dwordx2 v[192:193], v[184:185], off
	v_cvt_pk_bf16_f32 v186, v54, v55
	v_cvt_pk_bf16_f32 v187, v56, v57
	global_store_dwordx2 v[192:193], v[186:187], off offset:32
	v_cvt_pk_bf16_f32 v188, v58, v59
	v_cvt_pk_bf16_f32 v189, v60, v61
	global_store_dwordx2 v[192:193], v[188:189], off offset:64
	v_cvt_pk_bf16_f32 v190, v62, v63
	v_cvt_pk_bf16_f32 v191, v64, v65
	global_store_dwordx2 v[192:193], v[190:191], off offset:96
	v_cvt_pk_bf16_f32 v184, v66, v67
	v_cvt_pk_bf16_f32 v185, v68, v69
	global_store_dwordx2 v[192:193], v[184:185], off offset:128
	v_cvt_pk_bf16_f32 v186, v70, v71
	v_cvt_pk_bf16_f32 v187, v72, v73
	global_store_dwordx2 v[192:193], v[186:187], off offset:160
	v_cvt_pk_bf16_f32 v188, v74, v75
	v_cvt_pk_bf16_f32 v189, v76, v77
	global_store_dwordx2 v[192:193], v[188:189], off offset:192
	v_cvt_pk_bf16_f32 v190, v78, v79
	v_cvt_pk_bf16_f32 v191, v80, v81
	global_store_dwordx2 v[192:193], v[190:191], off offset:224
	s_cbranch_vccnz .LBB0_151
	s_add_i32 s8, s18, 0x80
	s_cmpk_gt_i32 s18, 0x77f
	s_mov_b32 s18, s8
	s_barrier
	s_cbranch_scc0 .LBB0_144

; DEVI void hgrn_a_item(int TID_, int BID_, PREF p, int item, char* shm) {
;     ...
;   const int w = tid >> 6, lane = tid & 63, fr = lane & 15, fq = lane >> 4;
; #pragma unroll 1
;   for (int dir = 0; dir < 2; ++dir) {
;     f32x4 acc[8];
; #pragma unroll
;     for (int n = 0; n < 8; ++n) acc[n] = (f32x4){0.f, 0.f, 0.f, 0.f};
; #pragma unroll
;     for (int ks = 0; ks < 2; ++ks) {
;       bf16x8 a = *(const bf16x8*)(vT + (16 * w + fr) * 72 + ks * 32 + fq * 8);
; #pragma unroll
;       for (int n = 0; n < 8; ++n) {
;         bf16x8 b = *(const bf16x8*)(kdT + (size_t)(dir * 128 + 16 * n + fr) * 72 + ks * 32 + fq * 8);
;         acc[n] = __builtin_amdgcn_mfma_f32_16x16x32_bf16(a, b, acc[n], 0, 0, 0);
;       }
;     }
;     u16* dst = upd + ((size_t)(c * 8 + h) * 2 + dir) * 16384;
; #pragma unroll
;     for (int n = 0; n < 8; ++n)
; #pragma unroll
;       for (int r = 0; r < 4; ++r) dst[(16 * w + fq * 4 + r) * 128 + 16 * n + fr] = f2bf(acc[n][r]);
;   }
.LBB0_463:
	v_lshl_or_b32 v10, s4, 7, v106
	v_mad_u32_u24 v10, v10, s57, v46
	s_lshl_b32 s68, s4, 15
	s_mov_b32 s4, 1
	s_and_b64 vcc, exec, s[36:37]
	s_mov_b64 s[36:37], 0
	ds_read_b128 v[146:149], v10 offset:18432
	ds_read_b128 v[150:153], v10 offset:20736
	ds_read_b128 v[154:157], v10 offset:23040
	ds_read_b128 v[158:161], v10 offset:25344
	ds_read_b128 v[162:165], v10 offset:27648
	ds_read_b128 v[166:169], v10 offset:29952
	ds_read_b128 v[170:173], v10 offset:32256
	ds_read_b128 v[174:177], v10 offset:34560
	ds_read_b128 v[184:187], v10 offset:18496
	ds_read_b128 v[188:191], v10 offset:20800
	ds_read_b128 v[192:195], v10 offset:23104
	ds_read_b128 v[216:219], v10 offset:25408
	s_waitcnt lgkmcnt(4)
	v_mfma_f32_16x16x32_bf16 v[146:149], v[146:149], v[0:3], 0
	v_mfma_f32_16x16x32_bf16 v[150:153], v[150:153], v[0:3], 0
	v_mfma_f32_16x16x32_bf16 v[154:157], v[154:157], v[0:3], 0
	v_mfma_f32_16x16x32_bf16 v[158:161], v[158:161], v[0:3], 0
	v_mfma_f32_16x16x32_bf16 v[162:165], v[162:165], v[0:3], 0
	v_mfma_f32_16x16x32_bf16 v[166:169], v[166:169], v[0:3], 0
	v_mfma_f32_16x16x32_bf16 v[170:173], v[170:173], v[0:3], 0
	v_mfma_f32_16x16x32_bf16 v[174:177], v[174:177], v[0:3], 0
	ds_read_b128 v[220:223], v10 offset:27712
	ds_read_b128 v[224:227], v10 offset:30016
	ds_read_b128 v[228:231], v10 offset:32320
	ds_read_b128 v[232:235], v10 offset:34624
	s_waitcnt lgkmcnt(4)
	v_mfma_f32_16x16x32_bf16 v[146:149], v[184:187], v[4:7], v[146:149]
	v_mfma_f32_16x16x32_bf16 v[150:153], v[188:191], v[4:7], v[150:153]
	v_mfma_f32_16x16x32_bf16 v[154:157], v[192:195], v[4:7], v[154:157]
	v_mfma_f32_16x16x32_bf16 v[158:161], v[216:219], v[4:7], v[158:161]
	s_waitcnt lgkmcnt(0)
	v_mfma_f32_16x16x32_bf16 v[162:165], v[220:223], v[4:7], v[162:165]
	v_mfma_f32_16x16x32_bf16 v[166:169], v[224:227], v[4:7], v[166:169]
	v_mfma_f32_16x16x32_bf16 v[170:173], v[228:231], v[4:7], v[170:173]
	v_mfma_f32_16x16x32_bf16 v[174:177], v[232:235], v[4:7], v[174:177]
	v_and_b32_e32 v194, 15, v203
	v_lshl_add_u32 v194, s48, 4, v194
	v_lshlrev_b32_e32 v194, 8, v194
	v_lshrrev_b32_e32 v195, 4, v203
	v_lshl_add_u32 v194, v195, 3, v194
	v_mov_b32_e32 v195, v197
	v_lshl_add_u64 v[192:193], v[8:9], 0, s[68:69]
	v_lshl_add_u64 v[192:193], v[192:193], 0, v[194:195]
	v_cvt_pk_bf16_f32 v184, v146, v147
	v_cvt_pk_bf16_f32 v185, v148, v149
	global_store_dwordx2 v[192:193], v[184:185], off
	v_cvt_pk_bf16_f32 v186, v150, v151
	v_cvt_pk_bf16_f32 v187, v152, v153
	global_store_dwordx2 v[192:193], v[186:187], off offset:32
	v_cvt_pk_bf16_f32 v188, v154, v155
	v_cvt_pk_bf16_f32 v189, v156, v157
	global_store_dwordx2 v[192:193], v[188:189], off offset:64
	v_cvt_pk_bf16_f32 v190, v158, v159
	v_cvt_pk_bf16_f32 v191, v160, v161
	global_store_dwordx2 v[192:193], v[190:191], off offset:96
	v_cvt_pk_bf16_f32 v184, v162, v163
	v_cvt_pk_bf16_f32 v185, v164, v165
	global_store_dwordx2 v[192:193], v[184:185], off offset:128
	v_cvt_pk_bf16_f32 v186, v166, v167
	v_cvt_pk_bf16_f32 v187, v168, v169
	global_store_dwordx2 v[192:193], v[186:187], off offset:160
	v_cvt_pk_bf16_f32 v188, v170, v171
	v_cvt_pk_bf16_f32 v189, v172, v173
	global_store_dwordx2 v[192:193], v[188:189], off offset:192
	v_cvt_pk_bf16_f32 v190, v174, v175
	v_cvt_pk_bf16_f32 v191, v176, v177
	global_store_dwordx2 v[192:193], v[190:191], off offset:224
	s_cbranch_vccnz .LBB0_463
	s_barrier
	s_branch .LBB0_254
